# SwiGLU epilogue: 8 serialized part loads + rstd chains hoisted to epilogue head (one wait)
# speedup vs baseline: 1.0227x; 1.0227x over previous
.LBB0_612:
	s_and_b64 vcc, exec, s[8:9]
	s_cbranch_vccz .LBB0_611
	v_lshlrev_b64 v[154:155], 6, v[150:151]
	v_lshl_add_u64 v[154:155], v[142:143], 0, v[154:155]
	v_add_co_u32_e32 v156, vcc, 0x2000, v154
	s_nop 1
	v_addc_co_u32_e32 v157, vcc, 0, v155, vcc
	global_load_dwordx4 v[170:173], v[154:155], off
	global_load_dwordx4 v[174:177], v[154:155], off offset:1024
	global_load_dwordx4 v[178:181], v[154:155], off offset:2048
	global_load_dwordx4 v[182:185], v[154:155], off offset:3072
	global_load_dwordx4 v[186:189], v[156:157], off
	global_load_dwordx4 v[200:203], v[156:157], off offset:1024
	global_load_dwordx4 v[204:207], v[156:157], off offset:2048
	global_load_dwordx4 v[208:211], v[156:157], off offset:3072
	v_or_b32_e32 v152, s91, v136
	v_lshl_or_b32 v152, s14, 7, v152
	v_ashrrev_i32_e32 v153, 31, v152
	s_waitcnt vmcnt(0)
	v_add_f32_e32 v170, v171, v170
	v_add_f32_e32 v172, v172, v173
	v_add_f32_e32 v174, v175, v174
	v_add_f32_e32 v176, v176, v177
	v_add_f32_e32 v178, v179, v178
	v_add_f32_e32 v180, v180, v181
	v_add_f32_e32 v182, v183, v182
	v_add_f32_e32 v184, v184, v185
	v_add_f32_e32 v186, v187, v186
	v_add_f32_e32 v188, v188, v189
	v_add_f32_e32 v200, v201, v200
	v_add_f32_e32 v202, v202, v203
	v_add_f32_e32 v204, v205, v204
	v_add_f32_e32 v206, v206, v207
	v_add_f32_e32 v208, v209, v208
	v_add_f32_e32 v210, v210, v211
	v_add_f32_e32 v170, v170, v172
	v_add_f32_e32 v174, v174, v176
	v_add_f32_e32 v178, v178, v180
	v_add_f32_e32 v182, v182, v184
	v_add_f32_e32 v186, v186, v188
	v_add_f32_e32 v200, v200, v202
	v_add_f32_e32 v204, v204, v206
	v_add_f32_e32 v208, v208, v210
	ds_bpermute_b32 v171, v197, v170
	ds_bpermute_b32 v175, v197, v174
	ds_bpermute_b32 v179, v197, v178
	ds_bpermute_b32 v183, v197, v182
	ds_bpermute_b32 v187, v197, v186
	ds_bpermute_b32 v201, v197, v200
	ds_bpermute_b32 v205, v197, v204
	ds_bpermute_b32 v209, v197, v208
	s_waitcnt lgkmcnt(0)
	v_add_f32_e32 v170, v170, v171
	v_add_f32_e32 v174, v174, v175
	v_add_f32_e32 v178, v178, v179
	v_add_f32_e32 v182, v182, v183
	v_add_f32_e32 v186, v186, v187
	v_add_f32_e32 v200, v200, v201
	v_add_f32_e32 v204, v204, v205
	v_add_f32_e32 v208, v208, v209
	ds_bpermute_b32 v171, v198, v170
	ds_bpermute_b32 v175, v198, v174
	ds_bpermute_b32 v179, v198, v178
	ds_bpermute_b32 v183, v198, v182
	ds_bpermute_b32 v187, v198, v186
	ds_bpermute_b32 v201, v198, v200
	ds_bpermute_b32 v205, v198, v204
	ds_bpermute_b32 v209, v198, v208
	s_waitcnt lgkmcnt(0)
	v_add_f32_e32 v170, v170, v171
	v_add_f32_e32 v174, v174, v175
	v_add_f32_e32 v178, v178, v179
	v_add_f32_e32 v182, v182, v183
	v_add_f32_e32 v186, v186, v187
	v_add_f32_e32 v200, v200, v201
	v_add_f32_e32 v204, v204, v205
	v_add_f32_e32 v208, v208, v209
	v_fmamk_f32 v170, v170, 0x3a800000, v216
	v_fmamk_f32 v174, v174, 0x3a800000, v216
	v_fmamk_f32 v178, v178, 0x3a800000, v216
	v_fmamk_f32 v182, v182, 0x3a800000, v216
	v_fmamk_f32 v186, v186, 0x3a800000, v216
	v_fmamk_f32 v200, v200, 0x3a800000, v216
	v_fmamk_f32 v204, v204, 0x3a800000, v216
	v_fmamk_f32 v208, v208, 0x3a800000, v216
	v_cmp_gt_f32_e32 vcc, s29, v170
	v_mul_f32_e32 v171, 0x4b800000, v170
	s_nop 0
	v_cndmask_b32_e32 v170, v170, v171, vcc
	v_rsq_f32_e32 v170, v170
	s_nop 0
	v_mul_f32_e32 v171, 0x45800000, v170
	v_cndmask_b32_e32 v170, v170, v171, vcc
	v_cmp_gt_f32_e32 vcc, s29, v174
	v_mul_f32_e32 v175, 0x4b800000, v174
	s_nop 0
	v_cndmask_b32_e32 v174, v174, v175, vcc
	v_rsq_f32_e32 v174, v174
	s_nop 0
	v_mul_f32_e32 v175, 0x45800000, v174
	v_cndmask_b32_e32 v174, v174, v175, vcc
	v_cmp_gt_f32_e32 vcc, s29, v178
	v_mul_f32_e32 v179, 0x4b800000, v178
	s_nop 0
	v_cndmask_b32_e32 v178, v178, v179, vcc
	v_rsq_f32_e32 v178, v178
	s_nop 0
	v_mul_f32_e32 v179, 0x45800000, v178
	v_cndmask_b32_e32 v178, v178, v179, vcc
	v_cmp_gt_f32_e32 vcc, s29, v182
	v_mul_f32_e32 v183, 0x4b800000, v182
	s_nop 0
	v_cndmask_b32_e32 v182, v182, v183, vcc
	v_rsq_f32_e32 v182, v182
	s_nop 0
	v_mul_f32_e32 v183, 0x45800000, v182
	v_cndmask_b32_e32 v182, v182, v183, vcc
	v_cmp_gt_f32_e32 vcc, s29, v186
	v_mul_f32_e32 v187, 0x4b800000, v186
	s_nop 0
	v_cndmask_b32_e32 v186, v186, v187, vcc
	v_rsq_f32_e32 v186, v186
	s_nop 0
	v_mul_f32_e32 v187, 0x45800000, v186
	v_cndmask_b32_e32 v186, v186, v187, vcc
	v_cmp_gt_f32_e32 vcc, s29, v200
	v_mul_f32_e32 v201, 0x4b800000, v200
	s_nop 0
	v_cndmask_b32_e32 v200, v200, v201, vcc
	v_rsq_f32_e32 v200, v200
	s_nop 0
	v_mul_f32_e32 v201, 0x45800000, v200
	v_cndmask_b32_e32 v200, v200, v201, vcc
	v_cmp_gt_f32_e32 vcc, s29, v204
	v_mul_f32_e32 v205, 0x4b800000, v204
	s_nop 0
	v_cndmask_b32_e32 v204, v204, v205, vcc
	v_rsq_f32_e32 v204, v204
	s_nop 0
	v_mul_f32_e32 v205, 0x45800000, v204
	v_cndmask_b32_e32 v204, v204, v205, vcc
	v_cmp_gt_f32_e32 vcc, s29, v208
	v_mul_f32_e32 v209, 0x4b800000, v208
	s_nop 0
	v_cndmask_b32_e32 v208, v208, v209, vcc
	v_rsq_f32_e32 v208, v208
	s_nop 0
	v_mul_f32_e32 v209, 0x45800000, v208
	v_cndmask_b32_e32 v208, v208, v209, vcc
	v_mov_b32_e32 v154, v170
	v_pk_mul_f32 v[124:125], v[124:125], v[154:155] op_sel_hi:[1,0]
	v_pk_mul_f32 v[116:117], v[116:117], v[154:155] op_sel_hi:[1,0]
	v_mul_f32_e32 v151, 0xbfb8aa3b, v124
	v_pk_mul_f32 v[116:117], v[124:125], v[116:117]
	v_mul_f32_e32 v124, 0xbfb8aa3b, v125
	v_exp_f32_e32 v124, v124
	v_pk_mul_f32 v[118:119], v[118:119], v[154:155] op_sel_hi:[1,0]
	v_pk_mul_f32 v[120:121], v[120:121], v[154:155] op_sel_hi:[1,0]
	v_pk_mul_f32 v[112:113], v[112:113], v[154:155] op_sel_hi:[1,0]
	v_add_f32_e32 v124, 1.0, v124
	v_rcp_f32_e32 v157, v124
	v_pk_mul_f32 v[124:125], v[126:127], v[154:155] op_sel_hi:[1,0]
	v_pk_mul_f32 v[112:113], v[120:121], v[112:113]
	v_mul_f32_e32 v126, 0xbfb8aa3b, v124
	v_pk_mul_f32 v[118:119], v[124:125], v[118:119]
	v_mul_f32_e32 v124, 0xbfb8aa3b, v125
	v_exp_f32_e32 v124, v124
	v_exp_f32_e32 v126, v126
	v_pk_mul_f32 v[114:115], v[114:115], v[154:155] op_sel_hi:[1,0]
	v_exp_f32_e32 v151, v151
	v_add_f32_e32 v124, 1.0, v124
	v_rcp_f32_e32 v127, v124
	v_mul_f32_e32 v124, 0xbfb8aa3b, v120
	v_mul_f32_e32 v120, 0xbfb8aa3b, v121
	v_exp_f32_e32 v124, v124
	v_exp_f32_e32 v120, v120
	v_add_f32_e32 v126, 1.0, v126
	v_add_f32_e32 v151, 1.0, v151
	v_add_f32_e32 v124, 1.0, v124
	v_add_f32_e32 v120, 1.0, v120
	v_rcp_f32_e32 v124, v124
	v_rcp_f32_e32 v125, v120
	v_rcp_f32_e32 v126, v126
	v_rcp_f32_e32 v156, v151
	v_pk_mul_f32 v[120:121], v[112:113], v[124:125]
	v_pk_mul_f32 v[112:113], v[122:123], v[154:155] op_sel_hi:[1,0]
	v_pk_mul_f32 v[118:119], v[118:119], v[126:127]
	v_mul_f32_e32 v122, 0xbfb8aa3b, v112
	v_pk_mul_f32 v[114:115], v[112:113], v[114:115]
	v_mul_f32_e32 v112, 0xbfb8aa3b, v113
	v_exp_f32_e32 v122, v122
	v_exp_f32_e32 v112, v112
	v_pk_mul_f32 v[116:117], v[116:117], v[156:157]
	v_cvt_pk_bf16_f32 v113, v118, v119
	v_add_f32_e32 v122, 1.0, v122
	v_add_f32_e32 v112, 1.0, v112
	v_rcp_f32_e32 v122, v122
	v_rcp_f32_e32 v123, v112
	v_mov_b64_e32 v[118:119], s[64:65]
	v_cvt_pk_bf16_f32 v112, v116, v117
	v_lshlrev_b64 v[116:117], 1, v[152:153]
	v_pk_mul_f32 v[122:123], v[114:115], v[122:123]
	v_cvt_pk_bf16_f32 v114, v120, v121
	v_mad_i64_i32 v[120:121], s[8:9], v150, s72, v[118:119]
	v_cvt_pk_bf16_f32 v115, v122, v123
	v_lshl_add_u64 v[120:121], v[120:121], 0, v[116:117]
	global_store_dwordx4 v[120:121], v[112:115], off
	s_nop 1
	v_or_b32_e32 v112, 16, v150
	v_mov_b32_e32 v114, v174
	v_pk_mul_f32 v[108:109], v[108:109], v[114:115] op_sel_hi:[1,0]
	v_pk_mul_f32 v[100:101], v[100:101], v[114:115] op_sel_hi:[1,0]
	v_mul_f32_e32 v113, 0xbfb8aa3b, v108
	v_pk_mul_f32 v[100:101], v[108:109], v[100:101]
	v_mul_f32_e32 v108, 0xbfb8aa3b, v109
	v_exp_f32_e32 v108, v108
	v_pk_mul_f32 v[102:103], v[102:103], v[114:115] op_sel_hi:[1,0]
	v_pk_mul_f32 v[104:105], v[104:105], v[114:115] op_sel_hi:[1,0]
	v_pk_mul_f32 v[96:97], v[96:97], v[114:115] op_sel_hi:[1,0]
	v_add_f32_e32 v108, 1.0, v108
	v_rcp_f32_e32 v121, v108
	v_pk_mul_f32 v[108:109], v[110:111], v[114:115] op_sel_hi:[1,0]
	v_pk_mul_f32 v[96:97], v[104:105], v[96:97]
	v_mul_f32_e32 v110, 0xbfb8aa3b, v108
	v_pk_mul_f32 v[102:103], v[108:109], v[102:103]
	v_mul_f32_e32 v108, 0xbfb8aa3b, v109
	v_exp_f32_e32 v108, v108
	v_pk_mul_f32 v[98:99], v[98:99], v[114:115] op_sel_hi:[1,0]
	v_exp_f32_e32 v113, v113
	v_exp_f32_e32 v110, v110
	v_add_f32_e32 v108, 1.0, v108
	v_rcp_f32_e32 v111, v108
	v_mul_f32_e32 v108, 0xbfb8aa3b, v104
	v_mul_f32_e32 v104, 0xbfb8aa3b, v105
	v_exp_f32_e32 v108, v108
	v_exp_f32_e32 v104, v104
	v_add_f32_e32 v113, 1.0, v113
	v_rcp_f32_e32 v120, v113
	v_add_f32_e32 v108, 1.0, v108
	v_add_f32_e32 v104, 1.0, v104
	v_rcp_f32_e32 v108, v108
	v_rcp_f32_e32 v109, v104
	v_add_f32_e32 v110, 1.0, v110
	v_rcp_f32_e32 v110, v110
	v_pk_mul_f32 v[100:101], v[100:101], v[120:121]
	v_pk_mul_f32 v[104:105], v[96:97], v[108:109]
	v_pk_mul_f32 v[96:97], v[106:107], v[114:115] op_sel_hi:[1,0]
	v_pk_mul_f32 v[102:103], v[102:103], v[110:111]
	v_mul_f32_e32 v106, 0xbfb8aa3b, v96
	v_pk_mul_f32 v[98:99], v[96:97], v[98:99]
	v_mul_f32_e32 v96, 0xbfb8aa3b, v97
	v_exp_f32_e32 v106, v106
	v_exp_f32_e32 v96, v96
	v_cvt_pk_bf16_f32 v97, v102, v103
	v_add_f32_e32 v106, 1.0, v106
	v_add_f32_e32 v96, 1.0, v96
	v_rcp_f32_e32 v106, v106
	v_rcp_f32_e32 v107, v96
	v_cvt_pk_bf16_f32 v96, v100, v101
	v_mad_i64_i32 v[100:101], s[8:9], v112, s72, v[118:119]
	v_pk_mul_f32 v[106:107], v[98:99], v[106:107]
	v_cvt_pk_bf16_f32 v98, v104, v105
	v_cvt_pk_bf16_f32 v99, v106, v107
	v_lshl_add_u64 v[100:101], v[100:101], 0, v[116:117]
	global_store_dwordx4 v[100:101], v[96:99], off
	s_nop 1
	v_or_b32_e32 v96, 32, v150
	v_mov_b32_e32 v98, v178
	v_pk_mul_f32 v[92:93], v[92:93], v[98:99] op_sel_hi:[1,0]
	v_pk_mul_f32 v[84:85], v[84:85], v[98:99] op_sel_hi:[1,0]
	v_mul_f32_e32 v97, 0xbfb8aa3b, v92
	v_pk_mul_f32 v[84:85], v[92:93], v[84:85]
	v_mul_f32_e32 v92, 0xbfb8aa3b, v93
	v_exp_f32_e32 v92, v92
	v_pk_mul_f32 v[86:87], v[86:87], v[98:99] op_sel_hi:[1,0]
	v_pk_mul_f32 v[88:89], v[88:89], v[98:99] op_sel_hi:[1,0]
	v_pk_mul_f32 v[80:81], v[80:81], v[98:99] op_sel_hi:[1,0]
	v_add_f32_e32 v92, 1.0, v92
	v_rcp_f32_e32 v101, v92
	v_pk_mul_f32 v[92:93], v[94:95], v[98:99] op_sel_hi:[1,0]
	v_pk_mul_f32 v[80:81], v[88:89], v[80:81]
	v_mul_f32_e32 v94, 0xbfb8aa3b, v92
	v_pk_mul_f32 v[86:87], v[92:93], v[86:87]
	v_mul_f32_e32 v92, 0xbfb8aa3b, v93
	v_exp_f32_e32 v92, v92
	v_pk_mul_f32 v[82:83], v[82:83], v[98:99] op_sel_hi:[1,0]
	v_exp_f32_e32 v97, v97
	v_exp_f32_e32 v94, v94
	v_add_f32_e32 v92, 1.0, v92
	v_rcp_f32_e32 v95, v92
	v_mul_f32_e32 v92, 0xbfb8aa3b, v88
	v_mul_f32_e32 v88, 0xbfb8aa3b, v89
	v_exp_f32_e32 v92, v92
	v_exp_f32_e32 v88, v88
	v_add_f32_e32 v97, 1.0, v97
	v_rcp_f32_e32 v100, v97
	v_add_f32_e32 v92, 1.0, v92
	v_add_f32_e32 v88, 1.0, v88
	v_rcp_f32_e32 v92, v92
	v_rcp_f32_e32 v93, v88
	v_add_f32_e32 v94, 1.0, v94
	v_rcp_f32_e32 v94, v94
	v_pk_mul_f32 v[84:85], v[84:85], v[100:101]
	v_pk_mul_f32 v[88:89], v[80:81], v[92:93]
	v_pk_mul_f32 v[80:81], v[90:91], v[98:99] op_sel_hi:[1,0]
	v_pk_mul_f32 v[86:87], v[86:87], v[94:95]
	v_mul_f32_e32 v90, 0xbfb8aa3b, v80
	v_pk_mul_f32 v[82:83], v[80:81], v[82:83]
	v_mul_f32_e32 v80, 0xbfb8aa3b, v81
	v_exp_f32_e32 v90, v90
	v_exp_f32_e32 v80, v80
	v_cvt_pk_bf16_f32 v81, v86, v87
	v_add_f32_e32 v90, 1.0, v90
	v_add_f32_e32 v80, 1.0, v80
	v_rcp_f32_e32 v90, v90
	v_rcp_f32_e32 v91, v80
	v_cvt_pk_bf16_f32 v80, v84, v85
	v_mad_i64_i32 v[84:85], s[8:9], v96, s72, v[118:119]
	v_pk_mul_f32 v[90:91], v[82:83], v[90:91]
	v_cvt_pk_bf16_f32 v82, v88, v89
	v_cvt_pk_bf16_f32 v83, v90, v91
	v_lshl_add_u64 v[84:85], v[84:85], 0, v[116:117]
	global_store_dwordx4 v[84:85], v[80:83], off
	s_nop 1
	v_or_b32_e32 v80, 48, v150
	v_mov_b32_e32 v82, v182
	v_pk_mul_f32 v[76:77], v[76:77], v[82:83] op_sel_hi:[1,0]
	v_pk_mul_f32 v[68:69], v[68:69], v[82:83] op_sel_hi:[1,0]
	v_mul_f32_e32 v81, 0xbfb8aa3b, v76
	v_pk_mul_f32 v[68:69], v[76:77], v[68:69]
	v_mul_f32_e32 v76, 0xbfb8aa3b, v77
	v_exp_f32_e32 v76, v76
	v_pk_mul_f32 v[70:71], v[70:71], v[82:83] op_sel_hi:[1,0]
	v_pk_mul_f32 v[72:73], v[72:73], v[82:83] op_sel_hi:[1,0]
	v_pk_mul_f32 v[64:65], v[64:65], v[82:83] op_sel_hi:[1,0]
	v_add_f32_e32 v76, 1.0, v76
	v_rcp_f32_e32 v85, v76
	v_pk_mul_f32 v[76:77], v[78:79], v[82:83] op_sel_hi:[1,0]
	v_pk_mul_f32 v[64:65], v[72:73], v[64:65]
	v_mul_f32_e32 v78, 0xbfb8aa3b, v76
	v_pk_mul_f32 v[70:71], v[76:77], v[70:71]
	v_mul_f32_e32 v76, 0xbfb8aa3b, v77
	v_exp_f32_e32 v76, v76
	v_pk_mul_f32 v[66:67], v[66:67], v[82:83] op_sel_hi:[1,0]
	v_exp_f32_e32 v81, v81
	v_exp_f32_e32 v78, v78
	v_add_f32_e32 v76, 1.0, v76
	v_rcp_f32_e32 v79, v76
	v_mul_f32_e32 v76, 0xbfb8aa3b, v72
	v_mul_f32_e32 v72, 0xbfb8aa3b, v73
	v_exp_f32_e32 v76, v76
	v_exp_f32_e32 v72, v72
	v_add_f32_e32 v81, 1.0, v81
	v_rcp_f32_e32 v84, v81
	v_add_f32_e32 v76, 1.0, v76
	v_add_f32_e32 v72, 1.0, v72
	v_rcp_f32_e32 v76, v76
	v_rcp_f32_e32 v77, v72
	v_add_f32_e32 v78, 1.0, v78
	v_rcp_f32_e32 v78, v78
	v_pk_mul_f32 v[68:69], v[68:69], v[84:85]
	v_pk_mul_f32 v[72:73], v[64:65], v[76:77]
	v_pk_mul_f32 v[64:65], v[74:75], v[82:83] op_sel_hi:[1,0]
	v_pk_mul_f32 v[70:71], v[70:71], v[78:79]
	v_mul_f32_e32 v74, 0xbfb8aa3b, v64
	v_pk_mul_f32 v[66:67], v[64:65], v[66:67]
	v_mul_f32_e32 v64, 0xbfb8aa3b, v65
	v_exp_f32_e32 v74, v74
	v_exp_f32_e32 v64, v64
	v_cvt_pk_bf16_f32 v65, v70, v71
	v_add_f32_e32 v74, 1.0, v74
	v_add_f32_e32 v64, 1.0, v64
	v_rcp_f32_e32 v74, v74
	v_rcp_f32_e32 v75, v64
	v_cvt_pk_bf16_f32 v64, v68, v69
	v_mad_i64_i32 v[68:69], s[8:9], v80, s72, v[118:119]
	v_pk_mul_f32 v[74:75], v[66:67], v[74:75]
	v_cvt_pk_bf16_f32 v66, v72, v73
	v_cvt_pk_bf16_f32 v67, v74, v75
	v_lshl_add_u64 v[68:69], v[68:69], 0, v[116:117]
	global_store_dwordx4 v[68:69], v[64:67], off
	s_nop 1
	v_add_u32_e32 v64, 0x80, v150
	v_mov_b32_e32 v66, v186
	v_pk_mul_f32 v[60:61], v[60:61], v[66:67] op_sel_hi:[1,0]
	v_pk_mul_f32 v[52:53], v[52:53], v[66:67] op_sel_hi:[1,0]
	v_mul_f32_e32 v65, 0xbfb8aa3b, v60
	v_pk_mul_f32 v[52:53], v[60:61], v[52:53]
	v_mul_f32_e32 v60, 0xbfb8aa3b, v61
	v_exp_f32_e32 v60, v60
	v_pk_mul_f32 v[54:55], v[54:55], v[66:67] op_sel_hi:[1,0]
	v_pk_mul_f32 v[56:57], v[56:57], v[66:67] op_sel_hi:[1,0]
	v_pk_mul_f32 v[48:49], v[48:49], v[66:67] op_sel_hi:[1,0]
	v_add_f32_e32 v60, 1.0, v60
	v_rcp_f32_e32 v69, v60
	v_pk_mul_f32 v[60:61], v[62:63], v[66:67] op_sel_hi:[1,0]
	v_pk_mul_f32 v[48:49], v[56:57], v[48:49]
	v_mul_f32_e32 v62, 0xbfb8aa3b, v60
	v_pk_mul_f32 v[54:55], v[60:61], v[54:55]
	v_mul_f32_e32 v60, 0xbfb8aa3b, v61
	v_exp_f32_e32 v60, v60
	v_pk_mul_f32 v[50:51], v[50:51], v[66:67] op_sel_hi:[1,0]
	v_exp_f32_e32 v65, v65
	v_exp_f32_e32 v62, v62
	v_add_f32_e32 v60, 1.0, v60
	v_rcp_f32_e32 v63, v60
	v_mul_f32_e32 v60, 0xbfb8aa3b, v56
	v_mul_f32_e32 v56, 0xbfb8aa3b, v57
	v_exp_f32_e32 v60, v60
	v_exp_f32_e32 v56, v56
	v_add_f32_e32 v65, 1.0, v65
	v_rcp_f32_e32 v68, v65
	v_add_f32_e32 v60, 1.0, v60
	v_add_f32_e32 v56, 1.0, v56
	v_rcp_f32_e32 v60, v60
	v_rcp_f32_e32 v61, v56
	v_add_f32_e32 v62, 1.0, v62
	v_rcp_f32_e32 v62, v62
	v_pk_mul_f32 v[52:53], v[52:53], v[68:69]
	v_pk_mul_f32 v[56:57], v[48:49], v[60:61]
	v_pk_mul_f32 v[48:49], v[58:59], v[66:67] op_sel_hi:[1,0]
	v_pk_mul_f32 v[54:55], v[54:55], v[62:63]
	v_mul_f32_e32 v58, 0xbfb8aa3b, v48
	v_pk_mul_f32 v[50:51], v[48:49], v[50:51]
	v_mul_f32_e32 v48, 0xbfb8aa3b, v49
	v_exp_f32_e32 v58, v58
	v_exp_f32_e32 v48, v48
	v_cvt_pk_bf16_f32 v49, v54, v55
	v_add_f32_e32 v58, 1.0, v58
	v_add_f32_e32 v48, 1.0, v48
	v_rcp_f32_e32 v58, v58
	v_rcp_f32_e32 v59, v48
	v_cvt_pk_bf16_f32 v48, v52, v53
	v_mad_i64_i32 v[52:53], s[8:9], v64, s72, v[118:119]
	v_pk_mul_f32 v[58:59], v[50:51], v[58:59]
	v_cvt_pk_bf16_f32 v50, v56, v57
	v_cvt_pk_bf16_f32 v51, v58, v59
	v_lshl_add_u64 v[52:53], v[52:53], 0, v[116:117]
	global_store_dwordx4 v[52:53], v[48:51], off
	s_nop 1
	v_add_u32_e32 v48, 0x90, v150
	v_mov_b32_e32 v50, v200
	v_pk_mul_f32 v[44:45], v[44:45], v[50:51] op_sel_hi:[1,0]
	v_pk_mul_f32 v[36:37], v[36:37], v[50:51] op_sel_hi:[1,0]
	v_mul_f32_e32 v49, 0xbfb8aa3b, v44
	v_pk_mul_f32 v[36:37], v[44:45], v[36:37]
	v_mul_f32_e32 v44, 0xbfb8aa3b, v45
	v_exp_f32_e32 v44, v44
	v_pk_mul_f32 v[38:39], v[38:39], v[50:51] op_sel_hi:[1,0]
	v_pk_mul_f32 v[40:41], v[40:41], v[50:51] op_sel_hi:[1,0]
	v_pk_mul_f32 v[32:33], v[32:33], v[50:51] op_sel_hi:[1,0]
	v_add_f32_e32 v44, 1.0, v44
	v_rcp_f32_e32 v53, v44
	v_pk_mul_f32 v[44:45], v[46:47], v[50:51] op_sel_hi:[1,0]
	v_pk_mul_f32 v[32:33], v[40:41], v[32:33]
	v_mul_f32_e32 v46, 0xbfb8aa3b, v44
	v_pk_mul_f32 v[38:39], v[44:45], v[38:39]
	v_mul_f32_e32 v44, 0xbfb8aa3b, v45
	v_exp_f32_e32 v44, v44
	v_pk_mul_f32 v[34:35], v[34:35], v[50:51] op_sel_hi:[1,0]
	v_exp_f32_e32 v49, v49
	v_exp_f32_e32 v46, v46
	v_add_f32_e32 v44, 1.0, v44
	v_rcp_f32_e32 v47, v44
	v_mul_f32_e32 v44, 0xbfb8aa3b, v40
	v_mul_f32_e32 v40, 0xbfb8aa3b, v41
	v_exp_f32_e32 v44, v44
	v_exp_f32_e32 v40, v40
	v_add_f32_e32 v49, 1.0, v49
	v_rcp_f32_e32 v52, v49
	v_add_f32_e32 v44, 1.0, v44
	v_add_f32_e32 v40, 1.0, v40
	v_rcp_f32_e32 v44, v44
	v_rcp_f32_e32 v45, v40
	v_add_f32_e32 v46, 1.0, v46
	v_rcp_f32_e32 v46, v46
	v_pk_mul_f32 v[36:37], v[36:37], v[52:53]
	v_pk_mul_f32 v[40:41], v[32:33], v[44:45]
	v_pk_mul_f32 v[32:33], v[42:43], v[50:51] op_sel_hi:[1,0]
	v_pk_mul_f32 v[38:39], v[38:39], v[46:47]
	v_mul_f32_e32 v42, 0xbfb8aa3b, v32
	v_pk_mul_f32 v[34:35], v[32:33], v[34:35]
	v_mul_f32_e32 v32, 0xbfb8aa3b, v33
	v_exp_f32_e32 v42, v42
	v_exp_f32_e32 v32, v32
	v_cvt_pk_bf16_f32 v33, v38, v39
	v_add_f32_e32 v42, 1.0, v42
	v_add_f32_e32 v32, 1.0, v32
	v_rcp_f32_e32 v42, v42
	v_rcp_f32_e32 v43, v32
	v_cvt_pk_bf16_f32 v32, v36, v37
	v_mad_i64_i32 v[36:37], s[8:9], v48, s72, v[118:119]
	v_pk_mul_f32 v[42:43], v[34:35], v[42:43]
	v_cvt_pk_bf16_f32 v34, v40, v41
	v_cvt_pk_bf16_f32 v35, v42, v43
	v_lshl_add_u64 v[36:37], v[36:37], 0, v[116:117]
	global_store_dwordx4 v[36:37], v[32:35], off
	s_nop 1
	v_add_u32_e32 v32, 0xa0, v150
	v_mov_b32_e32 v34, v204
	v_pk_mul_f32 v[28:29], v[28:29], v[34:35] op_sel_hi:[1,0]
	v_pk_mul_f32 v[20:21], v[20:21], v[34:35] op_sel_hi:[1,0]
	v_mul_f32_e32 v33, 0xbfb8aa3b, v28
	v_pk_mul_f32 v[20:21], v[28:29], v[20:21]
	v_mul_f32_e32 v28, 0xbfb8aa3b, v29
	v_exp_f32_e32 v28, v28
	v_pk_mul_f32 v[22:23], v[22:23], v[34:35] op_sel_hi:[1,0]
	v_pk_mul_f32 v[24:25], v[24:25], v[34:35] op_sel_hi:[1,0]
	v_pk_mul_f32 v[16:17], v[16:17], v[34:35] op_sel_hi:[1,0]
	v_add_f32_e32 v28, 1.0, v28
	v_rcp_f32_e32 v37, v28
	v_pk_mul_f32 v[28:29], v[30:31], v[34:35] op_sel_hi:[1,0]
	v_pk_mul_f32 v[16:17], v[24:25], v[16:17]
	v_mul_f32_e32 v30, 0xbfb8aa3b, v28
	v_pk_mul_f32 v[22:23], v[28:29], v[22:23]
	v_mul_f32_e32 v28, 0xbfb8aa3b, v29
	v_exp_f32_e32 v28, v28
	v_pk_mul_f32 v[18:19], v[18:19], v[34:35] op_sel_hi:[1,0]
	v_exp_f32_e32 v33, v33
	v_exp_f32_e32 v30, v30
	v_add_f32_e32 v28, 1.0, v28
	v_rcp_f32_e32 v31, v28
	v_mul_f32_e32 v28, 0xbfb8aa3b, v24
	v_mul_f32_e32 v24, 0xbfb8aa3b, v25
	v_exp_f32_e32 v28, v28
	v_exp_f32_e32 v24, v24
	v_add_f32_e32 v33, 1.0, v33
	v_rcp_f32_e32 v36, v33
	v_add_f32_e32 v28, 1.0, v28
	v_add_f32_e32 v24, 1.0, v24
	v_rcp_f32_e32 v28, v28
	v_rcp_f32_e32 v29, v24
	v_add_f32_e32 v30, 1.0, v30
	v_rcp_f32_e32 v30, v30
	v_pk_mul_f32 v[20:21], v[20:21], v[36:37]
	v_pk_mul_f32 v[24:25], v[16:17], v[28:29]
	v_pk_mul_f32 v[16:17], v[26:27], v[34:35] op_sel_hi:[1,0]
	v_pk_mul_f32 v[22:23], v[22:23], v[30:31]
	v_mul_f32_e32 v26, 0xbfb8aa3b, v16
	v_pk_mul_f32 v[18:19], v[16:17], v[18:19]
	v_mul_f32_e32 v16, 0xbfb8aa3b, v17
	v_exp_f32_e32 v26, v26
	v_exp_f32_e32 v16, v16
	v_cvt_pk_bf16_f32 v17, v22, v23
	v_add_f32_e32 v26, 1.0, v26
	v_add_f32_e32 v16, 1.0, v16
	v_rcp_f32_e32 v26, v26
	v_rcp_f32_e32 v27, v16
	v_cvt_pk_bf16_f32 v16, v20, v21
	v_mad_i64_i32 v[20:21], s[8:9], v32, s72, v[118:119]
	v_pk_mul_f32 v[26:27], v[18:19], v[26:27]
	v_cvt_pk_bf16_f32 v18, v24, v25
	v_cvt_pk_bf16_f32 v19, v26, v27
	v_lshl_add_u64 v[20:21], v[20:21], 0, v[116:117]
	global_store_dwordx4 v[20:21], v[16:19], off
	s_nop 1
	v_add_u32_e32 v16, 0xb0, v150
	v_mov_b32_e32 v18, v208
	v_pk_mul_f32 v[12:13], v[12:13], v[18:19] op_sel_hi:[1,0]
	v_pk_mul_f32 v[4:5], v[4:5], v[18:19] op_sel_hi:[1,0]
	v_mul_f32_e32 v17, 0xbfb8aa3b, v12
	v_pk_mul_f32 v[4:5], v[12:13], v[4:5]
	v_mul_f32_e32 v12, 0xbfb8aa3b, v13
	v_exp_f32_e32 v12, v12
	v_pk_mul_f32 v[6:7], v[6:7], v[18:19] op_sel_hi:[1,0]
	v_pk_mul_f32 v[8:9], v[8:9], v[18:19] op_sel_hi:[1,0]
	v_pk_mul_f32 v[0:1], v[0:1], v[18:19] op_sel_hi:[1,0]
	v_add_f32_e32 v12, 1.0, v12
	v_rcp_f32_e32 v21, v12
	v_pk_mul_f32 v[12:13], v[14:15], v[18:19] op_sel_hi:[1,0]
	v_pk_mul_f32 v[0:1], v[8:9], v[0:1]
	v_mul_f32_e32 v14, 0xbfb8aa3b, v12
	v_pk_mul_f32 v[6:7], v[12:13], v[6:7]
	v_mul_f32_e32 v12, 0xbfb8aa3b, v13
	v_exp_f32_e32 v12, v12
	v_pk_mul_f32 v[2:3], v[2:3], v[18:19] op_sel_hi:[1,0]
	v_exp_f32_e32 v17, v17
	v_exp_f32_e32 v14, v14
	v_add_f32_e32 v12, 1.0, v12
	v_rcp_f32_e32 v15, v12
	v_mul_f32_e32 v12, 0xbfb8aa3b, v8
	v_mul_f32_e32 v8, 0xbfb8aa3b, v9
	v_exp_f32_e32 v12, v12
	v_exp_f32_e32 v8, v8
	v_add_f32_e32 v17, 1.0, v17
	v_rcp_f32_e32 v20, v17
	v_add_f32_e32 v12, 1.0, v12
	v_add_f32_e32 v8, 1.0, v8
	v_rcp_f32_e32 v12, v12
	v_rcp_f32_e32 v13, v8
	v_add_f32_e32 v14, 1.0, v14
	v_rcp_f32_e32 v14, v14
	v_pk_mul_f32 v[4:5], v[4:5], v[20:21]
	v_pk_mul_f32 v[8:9], v[0:1], v[12:13]
	v_pk_mul_f32 v[0:1], v[10:11], v[18:19] op_sel_hi:[1,0]
	v_pk_mul_f32 v[6:7], v[6:7], v[14:15]
	v_mul_f32_e32 v10, 0xbfb8aa3b, v0
	v_pk_mul_f32 v[2:3], v[0:1], v[2:3]
	v_mul_f32_e32 v0, 0xbfb8aa3b, v1
	v_exp_f32_e32 v10, v10
	v_exp_f32_e32 v0, v0
	v_cvt_pk_bf16_f32 v1, v6, v7
	v_add_f32_e32 v10, 1.0, v10
	v_add_f32_e32 v0, 1.0, v0
	v_rcp_f32_e32 v10, v10
	v_rcp_f32_e32 v11, v0
	v_cvt_pk_bf16_f32 v0, v4, v5
	v_mad_i64_i32 v[4:5], s[8:9], v16, s72, v[118:119]
	v_pk_mul_f32 v[10:11], v[2:3], v[10:11]
	v_cvt_pk_bf16_f32 v2, v8, v9
	v_cvt_pk_bf16_f32 v3, v10, v11
	v_lshl_add_u64 v[4:5], v[4:5], 0, v[116:117]
	global_store_dwordx4 v[4:5], v[0:3], off
	s_andn2_b64 vcc, exec, s[38:39]
	s_mov_b64 s[8:9], -1
	s_cbranch_vccnz .LBB0_474
